# P5 weight f32->bf16 transpose items rewritten by hand: 8 wide loads, LDS writes and reads each batched behind one wait
# speedup vs baseline: 1.1130x; 1.0224x over previous
.LBB0_410:
	s_or_b64 exec, exec, s[6:7]
	v_readfirstlane_b32 s26, v2
	s_cmpk_gt_u32 s26, 0x127f
	s_mov_b64 s[6:7], -1
	s_cbranch_scc1 .LBB0_405
	s_mov_b64 s[8:9], s[60:61]
	s_movk_i32 s10, 0x400
	s_mov_b32 s11, 0
	s_mov_b64 s[12:13], 0
	s_mov_b32 s14, 0x610000
	s_movk_i32 s15, 0x400
	s_mov_b32 s6, s26
	s_cmpk_lt_u32 s26, 0x200
	s_cbranch_scc1 .Lft_go
	s_sub_i32 s6, s26, 0x200
	s_mov_b64 s[8:9], s[64:65]
	s_movk_i32 s10, 0xb00
	s_mov_b32 s11, 1
	s_mov_b64 s[12:13], s[62:63]
	s_mov_b32 s14, 0x810000
	s_cmpk_lt_u32 s6, 0x580
	s_cbranch_scc1 .Lft_go
	s_sub_i32 s6, s6, 0x580
	s_mov_b64 s[8:9], s[66:67]
	s_mov_b32 s11, 2
	s_cmpk_lt_u32 s6, 0x580
	s_cbranch_scc1 .Lft_go
	s_sub_i32 s6, s6, 0x580
	s_mov_b64 s[8:9], s[28:29]
	s_movk_i32 s10, 0x400
	s_mov_b32 s11, 0
	s_mov_b64 s[12:13], 0
	s_mov_b32 s14, 0x1310000
	s_movk_i32 s15, 0xb00
.Lft_go:
	s_cmpk_eq_u32 s10, 0x400
	s_cbranch_scc0 .Lft_n88
	s_lshr_b32 s7, s6, 5
	s_and_b32 s48, s6, 31
	s_branch .Lft_kn
.Lft_n88:
	s_mul_i32 s7, s6, 0x2e9
	s_lshr_b32 s7, s7, 16
	s_mul_i32 s48, s7, 0x58
	s_sub_i32 s48, s6, s48
.Lft_kn:
	s_lshl_b32 s49, s7, 6
	s_lshl_b32 s52, s48, 5
	s_lshl_b32 s53, s10, 5
	s_add_u32 s42, s68, s14
	s_addc_u32 s43, s69, 0
	v_and_b32_e32 v0, 7, v182
	v_lshrrev_b32_e32 v1, 3, v182
	v_add_u32_e32 v2, s49, v1
	v_mul_lo_u32 v2, v2, s10
	v_lshl_add_u32 v15, v0, 2, s52
	v_add_lshl_u32 v2, v2, v15, 2
	global_load_dwordx4 v[16:19], v2, s[8:9]
	v_add_u32_e32 v2, s53, v2
	global_load_dwordx4 v[20:23], v2, s[8:9]
	v_add_u32_e32 v2, s53, v2
	global_load_dwordx4 v[24:27], v2, s[8:9]
	v_add_u32_e32 v2, s53, v2
	global_load_dwordx4 v[28:31], v2, s[8:9]
	v_add_u32_e32 v2, s53, v2
	global_load_dwordx4 v[32:35], v2, s[8:9]
	v_add_u32_e32 v2, s53, v2
	global_load_dwordx4 v[36:39], v2, s[8:9]
	v_add_u32_e32 v2, s53, v2
	global_load_dwordx4 v[40:43], v2, s[8:9]
	v_add_u32_e32 v2, s53, v2
	global_load_dwordx4 v[44:47], v2, s[8:9]
	s_cmp_lg_u64 s[12:13], 0
	s_cbranch_scc0 .Lft_noks
	v_add_lshl_u32 v4, s49, v1, 2
	global_load_dword v48, v4, s[12:13] offset:0
	global_load_dword v49, v4, s[12:13] offset:32
	global_load_dword v50, v4, s[12:13] offset:64
	global_load_dword v51, v4, s[12:13] offset:96
	global_load_dword v52, v4, s[12:13] offset:128
	global_load_dword v53, v4, s[12:13] offset:160
	global_load_dword v54, v4, s[12:13] offset:192
	global_load_dword v55, v4, s[12:13] offset:224
	s_waitcnt vmcnt(0)
	v_mul_f32_e32 v16, v16, v48
	v_mul_f32_e32 v17, v17, v48
	v_mul_f32_e32 v18, v18, v48
	v_mul_f32_e32 v19, v19, v48
	v_mul_f32_e32 v20, v20, v49
	v_mul_f32_e32 v21, v21, v49
	v_mul_f32_e32 v22, v22, v49
	v_mul_f32_e32 v23, v23, v49
	v_mul_f32_e32 v24, v24, v50
	v_mul_f32_e32 v25, v25, v50
	v_mul_f32_e32 v26, v26, v50
	v_mul_f32_e32 v27, v27, v50
	v_mul_f32_e32 v28, v28, v51
	v_mul_f32_e32 v29, v29, v51
	v_mul_f32_e32 v30, v30, v51
	v_mul_f32_e32 v31, v31, v51
	v_mul_f32_e32 v32, v32, v52
	v_mul_f32_e32 v33, v33, v52
	v_mul_f32_e32 v34, v34, v52
	v_mul_f32_e32 v35, v35, v52
	v_mul_f32_e32 v36, v36, v53
	v_mul_f32_e32 v37, v37, v53
	v_mul_f32_e32 v38, v38, v53
	v_mul_f32_e32 v39, v39, v53
	v_mul_f32_e32 v40, v40, v54
	v_mul_f32_e32 v41, v41, v54
	v_mul_f32_e32 v42, v42, v54
	v_mul_f32_e32 v43, v43, v54
	v_mul_f32_e32 v44, v44, v55
	v_mul_f32_e32 v45, v45, v55
	v_mul_f32_e32 v46, v46, v55
	v_mul_f32_e32 v47, v47, v55
.Lft_noks:
	v_mul_u32_u24_e32 v5, 33, v1
	v_lshl_add_u32 v5, v0, 2, v5
	v_lshl_add_u32 v5, v5, 2, s79
	v_mul_u32_u24_e32 v6, 0x108, v0
	v_add_u32_e32 v6, v6, v1
	v_lshl_add_u32 v6, v6, 2, s79
	s_waitcnt vmcnt(0)
	ds_write_b32 v5, v16 offset:0
	ds_write_b32 v5, v17 offset:4
	ds_write_b32 v5, v18 offset:8
	ds_write_b32 v5, v19 offset:12
	ds_write_b32 v5, v20 offset:1056
	ds_write_b32 v5, v21 offset:1060
	ds_write_b32 v5, v22 offset:1064
	ds_write_b32 v5, v23 offset:1068
	ds_write_b32 v5, v24 offset:2112
	ds_write_b32 v5, v25 offset:2116
	ds_write_b32 v5, v26 offset:2120
	ds_write_b32 v5, v27 offset:2124
	ds_write_b32 v5, v28 offset:3168
	ds_write_b32 v5, v29 offset:3172
	ds_write_b32 v5, v30 offset:3176
	ds_write_b32 v5, v31 offset:3180
	ds_write_b32 v5, v32 offset:4224
	ds_write_b32 v5, v33 offset:4228
	ds_write_b32 v5, v34 offset:4232
	ds_write_b32 v5, v35 offset:4236
	ds_write_b32 v5, v36 offset:5280
	ds_write_b32 v5, v37 offset:5284
	ds_write_b32 v5, v38 offset:5288
	ds_write_b32 v5, v39 offset:5292
	ds_write_b32 v5, v40 offset:6336
	ds_write_b32 v5, v41 offset:6340
	ds_write_b32 v5, v42 offset:6344
	ds_write_b32 v5, v43 offset:6348
	ds_write_b32 v5, v44 offset:7392
	ds_write_b32 v5, v45 offset:7396
	ds_write_b32 v5, v46 offset:7400
	ds_write_b32 v5, v47 offset:7404
	s_waitcnt lgkmcnt(0)
	ds_read_b32 v16, v6 offset:0
	ds_read_b32 v17, v6 offset:132
	ds_read_b32 v18, v6 offset:264
	ds_read_b32 v19, v6 offset:396
	ds_read_b32 v20, v6 offset:528
	ds_read_b32 v21, v6 offset:660
	ds_read_b32 v22, v6 offset:792
	ds_read_b32 v23, v6 offset:924
	ds_read_b32 v24, v6 offset:32
	ds_read_b32 v25, v6 offset:164
	ds_read_b32 v26, v6 offset:296
	ds_read_b32 v27, v6 offset:428
	ds_read_b32 v28, v6 offset:560
	ds_read_b32 v29, v6 offset:692
	ds_read_b32 v30, v6 offset:824
	ds_read_b32 v31, v6 offset:956
	ds_read_b32 v32, v6 offset:64
	ds_read_b32 v33, v6 offset:196
	ds_read_b32 v34, v6 offset:328
	ds_read_b32 v35, v6 offset:460
	ds_read_b32 v36, v6 offset:592
	ds_read_b32 v37, v6 offset:724
	ds_read_b32 v38, v6 offset:856
	ds_read_b32 v39, v6 offset:988
	ds_read_b32 v40, v6 offset:96
	ds_read_b32 v41, v6 offset:228
	ds_read_b32 v42, v6 offset:360
	ds_read_b32 v43, v6 offset:492
	ds_read_b32 v44, v6 offset:624
	ds_read_b32 v45, v6 offset:756
	ds_read_b32 v46, v6 offset:888
	ds_read_b32 v47, v6 offset:1020
	v_add_u32_e32 v7, s52, v1
	v_lshl_add_u32 v9, v0, 3, s49
	s_cmp_eq_u32 s11, 0
	s_cselect_b32 s54, 0, 1
	s_cmp_eq_u32 s11, 2
	s_cselect_b32 s55, 4, 0
	v_add_u32_e32 v10, 0, v7
	v_lshrrev_b32_e32 v8, 2, v10
	v_and_b32_e32 v14, 3, v10
	v_lshl_add_u32 v8, v8, 3, v14
	v_add_u32_e32 v8, s55, v8
	v_cmp_eq_u32_e64 vcc, s54, 1
	s_nop 1
	v_cndmask_b32_e32 v10, v10, v8, vcc
	v_mul_lo_u32 v10, v10, s15
	v_add_lshl_u32 v10, v10, v9, 1
	v_add_u32_e32 v11, 8, v7
	v_lshrrev_b32_e32 v8, 2, v11
	v_and_b32_e32 v14, 3, v11
	v_lshl_add_u32 v8, v8, 3, v14
	v_add_u32_e32 v8, s55, v8
	v_cmp_eq_u32_e64 vcc, s54, 1
	s_nop 1
	v_cndmask_b32_e32 v11, v11, v8, vcc
	v_mul_lo_u32 v11, v11, s15
	v_add_lshl_u32 v11, v11, v9, 1
	v_add_u32_e32 v12, 16, v7
	v_lshrrev_b32_e32 v8, 2, v12
	v_and_b32_e32 v14, 3, v12
	v_lshl_add_u32 v8, v8, 3, v14
	v_add_u32_e32 v8, s55, v8
	v_cmp_eq_u32_e64 vcc, s54, 1
	s_nop 1
	v_cndmask_b32_e32 v12, v12, v8, vcc
	v_mul_lo_u32 v12, v12, s15
	v_add_lshl_u32 v12, v12, v9, 1
	v_add_u32_e32 v13, 24, v7
	v_lshrrev_b32_e32 v8, 2, v13
	v_and_b32_e32 v14, 3, v13
	v_lshl_add_u32 v8, v8, 3, v14
	v_add_u32_e32 v8, s55, v8
	v_cmp_eq_u32_e64 vcc, s54, 1
	s_nop 1
	v_cndmask_b32_e32 v13, v13, v8, vcc
	v_mul_lo_u32 v13, v13, s15
	v_add_lshl_u32 v13, v13, v9, 1
	s_waitcnt lgkmcnt(0)
	v_cvt_pk_bf16_f32 v52, v16, v17
	v_cvt_pk_bf16_f32 v53, v18, v19
	v_cvt_pk_bf16_f32 v54, v20, v21
	v_cvt_pk_bf16_f32 v55, v22, v23
	v_cvt_pk_bf16_f32 v56, v24, v25
	v_cvt_pk_bf16_f32 v57, v26, v27
	v_cvt_pk_bf16_f32 v58, v28, v29
	v_cvt_pk_bf16_f32 v59, v30, v31
	v_cvt_pk_bf16_f32 v60, v32, v33
	v_cvt_pk_bf16_f32 v61, v34, v35
	v_cvt_pk_bf16_f32 v62, v36, v37
	v_cvt_pk_bf16_f32 v63, v38, v39
	v_cvt_pk_bf16_f32 v64, v40, v41
	v_cvt_pk_bf16_f32 v65, v42, v43
	v_cvt_pk_bf16_f32 v66, v44, v45
	v_cvt_pk_bf16_f32 v67, v46, v47
	global_store_dwordx4 v10, v[52:55], s[42:43]
	global_store_dwordx4 v11, v[56:59], s[42:43]
	global_store_dwordx4 v12, v[60:63], s[42:43]
	global_store_dwordx4 v13, v[64:67], s[42:43]
	s_branch .LBB0_404
